# P1 in-proj epilogue: cos/sin rows warm-up for the rope-key column tile (same idea as the q-up epilogue)
# speedup vs baseline: 1.0122x; 1.0022x over previous
.LBB0_232:
	s_cmp_lt_i32 s6, 3
	s_cbranch_scc1 .Levin_nowarm
	v_lshl_add_u32 v188, s8, 8, v153
	v_ashrrev_i32_e32 v189, 31, v188
	v_lshlrev_b64 v[188:189], 6, v[188:189]
	s_mov_b64 vcc, 0x1000
	v_lshl_add_u64 v[190:191], v[140:141], 0, v[188:189]
	v_lshl_add_u64 v[192:193], v[138:139], 0, v[188:189]
	v_lshl_add_u64 v[194:195], v[190:191], 0, vcc
	v_lshl_add_u64 v[196:197], v[192:193], 0, vcc
	global_load_dwordx4 v[184:187], v[190:191], off
	global_load_dwordx4 v[184:187], v[190:191], off offset:16
	global_load_dwordx4 v[184:187], v[190:191], off offset:1024
	global_load_dwordx4 v[184:187], v[190:191], off offset:1040
	global_load_dwordx4 v[184:187], v[190:191], off offset:2048
	global_load_dwordx4 v[184:187], v[190:191], off offset:2064
	global_load_dwordx4 v[184:187], v[190:191], off offset:3072
	global_load_dwordx4 v[184:187], v[190:191], off offset:3088
	global_load_dwordx4 v[184:187], v[192:193], off
	global_load_dwordx4 v[184:187], v[192:193], off offset:16
	global_load_dwordx4 v[184:187], v[192:193], off offset:1024
	global_load_dwordx4 v[184:187], v[192:193], off offset:1040
	global_load_dwordx4 v[184:187], v[192:193], off offset:2048
	global_load_dwordx4 v[184:187], v[192:193], off offset:2064
	global_load_dwordx4 v[184:187], v[192:193], off offset:3072
	global_load_dwordx4 v[184:187], v[192:193], off offset:3088
	global_load_dwordx4 v[184:187], v[194:195], off
	global_load_dwordx4 v[184:187], v[194:195], off offset:16
	global_load_dwordx4 v[184:187], v[194:195], off offset:1024
	global_load_dwordx4 v[184:187], v[194:195], off offset:1040
	global_load_dwordx4 v[184:187], v[194:195], off offset:2048
	global_load_dwordx4 v[184:187], v[194:195], off offset:2064
	global_load_dwordx4 v[184:187], v[194:195], off offset:3072
	global_load_dwordx4 v[184:187], v[194:195], off offset:3088
	global_load_dwordx4 v[184:187], v[196:197], off
	global_load_dwordx4 v[184:187], v[196:197], off offset:16
	global_load_dwordx4 v[184:187], v[196:197], off offset:1024
	global_load_dwordx4 v[184:187], v[196:197], off offset:1040
	global_load_dwordx4 v[184:187], v[196:197], off offset:2048
	global_load_dwordx4 v[184:187], v[196:197], off offset:2064
	global_load_dwordx4 v[184:187], v[196:197], off offset:3072
	global_load_dwordx4 v[184:187], v[196:197], off offset:3088
